# same as previous best, with wait states between a VALU-written SGPR mask and its scalar consumer in the phase-3 schedule setup
# baseline (speedup 1.0000x reference)
; DEVINL void run_phase(const Params& p, char* smem, int ph) {
;     ...
;       for (int it = bid; it < S5CP_BLK + GLAB_ITEMS + S5CS_BLK; it += nb) {
;         if (it < S5CP_BLK) { __syncthreads(); s5_passC_prompt(p, smem, it); }
;         else if (it < S5CP_BLK + GLAB_ITEMS) gla_passB(p, it - S5CP_BLK);
;         else { __syncthreads(); s5_passC_sample(p, smem, it - S5CP_BLK - GLAB_ITEMS); }
;       }
.LBB0_448:
	s_and_b64 vcc, exec, s[0:1]
	s_cbranch_vccz .LBB0_534
	s_cmpk_gt_i32 s14, 0xe7f
	s_cbranch_scc1 .LBB0_533
	s_lshl_b32 s0, s14, 5
	s_addk_i32 s0, 0xc000
	s_waitcnt vmcnt(0)
	v_lshlrev_b32_e32 v1, 5, v104
	s_mov_b64 s[40:41], 0
	s_waitcnt lgkmcnt(0)
	v_mov_b32_e32 v75, s14
	v_mov_b32_e32 v78, s0
	v_mov_b32_e32 v79, s14
	v_cmp_gt_u32_e32 vcc, 0x80, v79
	v_mov_b32_e32 v197, 0x200
	v_cmp_eq_u32_e64 s[0:1], v197, v104
	v_mov_b32_e32 v196, 0
	s_nop 3
	s_and_b64 vcc, vcc, s[0:1]
	v_mov_b32_e32 v197, 0x200
	s_nop 0
	v_cndmask_b32_e32 v196, v196, v197, vcc
	v_add_u32_e32 v79, v79, v196
	v_add_u16_e32 v75, v75, v196
	v_lshlrev_b32_e32 v197, 5, v196
	v_add_u32_e32 v78, v78, v197
	s_branch .LBB0_453
